# v124 without the trailing workgroup barrier at the arrive sites (waves 1-7 start the transpose slice while thread 0 signals)
# baseline (speedup 1.0000x reference)
.LBB0_125:
	s_or_b64 exec, exec, s[6:7]
	s_waitcnt lgkmcnt(0)
.LBB0_126:
	v_mov_b32_e32 v201, 0x24008
	ds_read_b32 v200, v201
	s_waitcnt lgkmcnt(0)
	s_cmp_lt_i32 s88, 1
	s_cbranch_scc0 .Lsl0_out
	s_cmp_gt_i32 s89, 0
	s_cbranch_scc0 .Lsl0_out
	s_load_dword s4, s[0:1], 0x120
	s_load_dwordx16 s[52:67], s[0:1], 0x0
	s_load_dwordx16 s[68:83], s[0:1], 0x80
	s_waitcnt lgkmcnt(0)
	s_add_u32 s98, s34, 0xed10500
	s_addc_u32 s99, s35, 0
	v_mov_b32_e32 v201, 0
	s_lshl_b32 s4, s4, 1
	s_mul_i32 s5, s4, 1
	s_lshl_b32 s33, s2, 1
	s_add_i32 s33, s33, s5
	s_cmp_eq_u32 s89, 18
	s_cselect_b32 s5, 2, 11
	s_mul_i32 s4, s4, s5
	s_min_u32 s4, s4, 0x15d0
	s_cmp_ge_i32 s33, s4
	s_cbranch_scc1 .Lsl0_out
	s_add_u32 s94, s34, 0x1da0000
	s_addc_u32 s95, s35, 0
	v_writelane_b32 v252, s90, 0
	s_add_u32 s4, s34, 0x7a0000
	s_addc_u32 s5, s35, 0
	v_writelane_b32 v252, s91, 1
	v_writelane_b32 v252, s4, 2
	v_lshrrev_b32_e32 v138, 8, v204
	v_and_b32_e32 v139, 0xff, v204
	v_writelane_b32 v252, s5, 3
	s_add_u32 s4, s34, 0x720000
	s_addc_u32 s5, s35, 0
	v_writelane_b32 v252, s4, 4
	v_mul_u32_u24_e32 v140, 0x12000, v138
	v_mov_b32_e32 v129, 0
	v_writelane_b32 v252, s5, 5
	s_add_u32 s4, s34, 0x520000
	s_addc_u32 s5, s35, 0
	s_add_u32 s90, s34, 0x4a0000
	s_addc_u32 s91, s35, 0
	s_add_u32 s96, s34, 0x440000
	s_addc_u32 s97, s35, 0
	s_add_u32 s16, s34, 0x28a0000
	s_addc_u32 s17, s35, 0
	s_add_u32 s18, s0, 0x120
	v_writelane_b32 v252, s4, 6
	s_addc_u32 s19, s1, 0
	s_movk_i32 s8, 0x104
	s_movk_i32 s9, 0xffe0
	s_movk_i32 s10, 0x6000
	s_movk_i32 s11, 0x400
	s_mov_b32 s12, 0xbfb8aa3b
	s_mov_b32 s13, 0x42ce8ed0
	s_mov_b32 s14, 0xc2b17218
	s_movk_i32 s15, 0x1800
	v_mov_b32_e32 v141, 0xfffffd40
	v_mov_b32_e32 v142, 0xb00000
	v_mov_b32_e32 v143, 0x580000
	v_mov_b32_e32 v144, 0x7f800000
	v_writelane_b32 v252, s5, 7
	s_branch .Lsl0_22

.LBB0_188:
	s_or_b64 exec, exec, s[6:7]
	s_waitcnt lgkmcnt(0)
.LBB0_189:
	v_mov_b32_e32 v201, 0x24008
	ds_read_b32 v200, v201
	s_waitcnt lgkmcnt(0)
	s_cmp_lg_u32 s88, 0
	s_cbranch_scc1 .Lsl1_out
	s_cmp_lg_u32 s89, 18
	s_cbranch_scc1 .Lsl1_out
	s_load_dword s4, s[0:1], 0x120
	s_load_dwordx16 s[52:67], s[0:1], 0x0
	s_load_dwordx16 s[68:83], s[0:1], 0x80
	s_waitcnt lgkmcnt(0)
	s_add_u32 s98, s34, 0xed10500
	s_addc_u32 s99, s35, 0
	v_mov_b32_e32 v201, 0
	s_lshl_b32 s4, s4, 1
	s_mul_i32 s5, s4, 2
	s_lshl_b32 s33, s2, 1
	s_add_i32 s33, s33, s5
	s_mov_b32 s5, 3
	s_mul_i32 s4, s4, s5
	s_min_u32 s4, s4, 0x15d0
	s_cmp_ge_i32 s33, s4
	s_cbranch_scc1 .Lsl1_out
	s_add_u32 s94, s34, 0x1da0000
	s_addc_u32 s95, s35, 0
	v_writelane_b32 v252, s90, 0
	s_add_u32 s4, s34, 0x7a0000
	s_addc_u32 s5, s35, 0
	v_writelane_b32 v252, s91, 1
	v_writelane_b32 v252, s4, 2
	v_lshrrev_b32_e32 v138, 8, v204
	v_and_b32_e32 v139, 0xff, v204
	v_writelane_b32 v252, s5, 3
	s_add_u32 s4, s34, 0x720000
	s_addc_u32 s5, s35, 0
	v_writelane_b32 v252, s4, 4
	v_mul_u32_u24_e32 v140, 0x12000, v138
	v_mov_b32_e32 v129, 0
	v_writelane_b32 v252, s5, 5
	s_add_u32 s4, s34, 0x520000
	s_addc_u32 s5, s35, 0
	s_add_u32 s90, s34, 0x4a0000
	s_addc_u32 s91, s35, 0
	s_add_u32 s96, s34, 0x440000
	s_addc_u32 s97, s35, 0
	s_add_u32 s16, s34, 0x28a0000
	s_addc_u32 s17, s35, 0
	s_add_u32 s18, s0, 0x120
	v_writelane_b32 v252, s4, 6
	s_addc_u32 s19, s1, 0
	s_movk_i32 s8, 0x104
	s_movk_i32 s9, 0xffe0
	s_movk_i32 s10, 0x6000
	s_movk_i32 s11, 0x400
	s_mov_b32 s12, 0xbfb8aa3b
	s_mov_b32 s13, 0x42ce8ed0
	s_mov_b32 s14, 0xc2b17218
	s_movk_i32 s15, 0x1800
	v_mov_b32_e32 v141, 0xfffffd40
	v_mov_b32_e32 v142, 0xb00000
	v_mov_b32_e32 v143, 0x580000
	v_mov_b32_e32 v144, 0x7f800000
	v_writelane_b32 v252, s5, 7
	s_branch .Lsl1_22

.LBB0_479:
	s_or_b64 exec, exec, s[6:7]
	s_waitcnt lgkmcnt(0)
.LBB0_480:
	v_mov_b32_e32 v201, 0x24008
	ds_read_b32 v200, v201
	s_waitcnt lgkmcnt(0)
	s_cmp_lg_u32 s88, 0
	s_cbranch_scc1 .Lsl2_out
	s_cmp_lg_u32 s89, 18
	s_cbranch_scc1 .Lsl2_out
	s_load_dword s4, s[0:1], 0x120
	s_load_dwordx16 s[52:67], s[0:1], 0x0
	s_load_dwordx16 s[68:83], s[0:1], 0x80
	s_waitcnt lgkmcnt(0)
	s_add_u32 s98, s34, 0xed10500
	s_addc_u32 s99, s35, 0
	v_mov_b32_e32 v201, 0
	s_lshl_b32 s4, s4, 1
	s_mul_i32 s5, s4, 3
	s_lshl_b32 s33, s2, 1
	s_add_i32 s33, s33, s5
	s_mov_b32 s5, 4
	s_mul_i32 s4, s4, s5
	s_min_u32 s4, s4, 0x15d0
	s_cmp_ge_i32 s33, s4
	s_cbranch_scc1 .Lsl2_out
	s_add_u32 s94, s34, 0x1da0000
	s_addc_u32 s95, s35, 0
	v_writelane_b32 v252, s90, 0
	s_add_u32 s4, s34, 0x7a0000
	s_addc_u32 s5, s35, 0
	v_writelane_b32 v252, s91, 1
	v_writelane_b32 v252, s4, 2
	v_lshrrev_b32_e32 v138, 8, v204
	v_and_b32_e32 v139, 0xff, v204
	v_writelane_b32 v252, s5, 3
	s_add_u32 s4, s34, 0x720000
	s_addc_u32 s5, s35, 0
	v_writelane_b32 v252, s4, 4
	v_mul_u32_u24_e32 v140, 0x12000, v138
	v_mov_b32_e32 v129, 0
	v_writelane_b32 v252, s5, 5
	s_add_u32 s4, s34, 0x520000
	s_addc_u32 s5, s35, 0
	s_add_u32 s90, s34, 0x4a0000
	s_addc_u32 s91, s35, 0
	s_add_u32 s96, s34, 0x440000
	s_addc_u32 s97, s35, 0
	s_add_u32 s16, s34, 0x28a0000
	s_addc_u32 s17, s35, 0
	s_add_u32 s18, s0, 0x120
	v_writelane_b32 v252, s4, 6
	s_addc_u32 s19, s1, 0
	s_movk_i32 s8, 0x104
	s_movk_i32 s9, 0xffe0
	s_movk_i32 s10, 0x6000
	s_movk_i32 s11, 0x400
	s_mov_b32 s12, 0xbfb8aa3b
	s_mov_b32 s13, 0x42ce8ed0
	s_mov_b32 s14, 0xc2b17218
	s_movk_i32 s15, 0x1800
	v_mov_b32_e32 v141, 0xfffffd40
	v_mov_b32_e32 v142, 0xb00000
	v_mov_b32_e32 v143, 0x580000
	v_mov_b32_e32 v144, 0x7f800000
	v_writelane_b32 v252, s5, 7
	s_branch .Lsl2_22

.LBB0_614:
	s_or_b64 exec, exec, s[6:7]
	s_waitcnt lgkmcnt(0)
.LBB0_615:
	v_mov_b32_e32 v201, 0x24008
	ds_read_b32 v200, v201
	s_waitcnt lgkmcnt(0)
	s_cmp_lg_u32 s88, 0
	s_cbranch_scc1 .Lsl3_out
	s_cmp_lg_u32 s89, 18
	s_cbranch_scc1 .Lsl3_out
	s_load_dword s4, s[0:1], 0x120
	s_load_dwordx16 s[52:67], s[0:1], 0x0
	s_load_dwordx16 s[68:83], s[0:1], 0x80
	s_waitcnt lgkmcnt(0)
	s_add_u32 s98, s34, 0xed10500
	s_addc_u32 s99, s35, 0
	v_mov_b32_e32 v201, 0
	s_lshl_b32 s4, s4, 1
	s_mul_i32 s5, s4, 4
	s_lshl_b32 s33, s2, 1
	s_add_i32 s33, s33, s5
	s_mov_b32 s5, 5
	s_mul_i32 s4, s4, s5
	s_min_u32 s4, s4, 0x15d0
	s_cmp_ge_i32 s33, s4
	s_cbranch_scc1 .Lsl3_out
	s_add_u32 s94, s34, 0x1da0000
	s_addc_u32 s95, s35, 0
	v_writelane_b32 v252, s90, 0
	s_add_u32 s4, s34, 0x7a0000
	s_addc_u32 s5, s35, 0
	v_writelane_b32 v252, s91, 1
	v_writelane_b32 v252, s4, 2
	v_lshrrev_b32_e32 v138, 8, v204
	v_and_b32_e32 v139, 0xff, v204
	v_writelane_b32 v252, s5, 3
	s_add_u32 s4, s34, 0x720000
	s_addc_u32 s5, s35, 0
	v_writelane_b32 v252, s4, 4
	v_mul_u32_u24_e32 v140, 0x12000, v138
	v_mov_b32_e32 v129, 0
	v_writelane_b32 v252, s5, 5
	s_add_u32 s4, s34, 0x520000
	s_addc_u32 s5, s35, 0
	s_add_u32 s90, s34, 0x4a0000
	s_addc_u32 s91, s35, 0
	s_add_u32 s96, s34, 0x440000
	s_addc_u32 s97, s35, 0
	s_add_u32 s16, s34, 0x28a0000
	s_addc_u32 s17, s35, 0
	s_add_u32 s18, s0, 0x120
	v_writelane_b32 v252, s4, 6
	s_addc_u32 s19, s1, 0
	s_movk_i32 s8, 0x104
	s_movk_i32 s9, 0xffe0
	s_movk_i32 s10, 0x6000
	s_movk_i32 s11, 0x400
	s_mov_b32 s12, 0xbfb8aa3b
	s_mov_b32 s13, 0x42ce8ed0
	s_mov_b32 s14, 0xc2b17218
	s_movk_i32 s15, 0x1800
	v_mov_b32_e32 v141, 0xfffffd40
	v_mov_b32_e32 v142, 0xb00000
	v_mov_b32_e32 v143, 0x580000
	v_mov_b32_e32 v144, 0x7f800000
	v_writelane_b32 v252, s5, 7
	s_branch .Lsl3_22

.LBB0_843:
	s_or_b64 exec, exec, s[6:7]
	s_waitcnt lgkmcnt(0)
.LBB0_844:
	v_mov_b32_e32 v201, 0x24008
	ds_read_b32 v200, v201
	s_waitcnt lgkmcnt(0)
	s_cmp_lg_u32 s88, 0
	s_cbranch_scc1 .Lsl4_out
	s_cmp_lg_u32 s89, 18
	s_cbranch_scc1 .Lsl4_out
	s_load_dword s4, s[0:1], 0x120
	s_load_dwordx16 s[52:67], s[0:1], 0x0
	s_load_dwordx16 s[68:83], s[0:1], 0x80
	s_waitcnt lgkmcnt(0)
	s_add_u32 s98, s34, 0xed10500
	s_addc_u32 s99, s35, 0
	v_mov_b32_e32 v201, 0
	s_lshl_b32 s4, s4, 1
	s_mul_i32 s5, s4, 5
	s_lshl_b32 s33, s2, 1
	s_add_i32 s33, s33, s5
	s_mov_b32 s5, 6
	s_mul_i32 s4, s4, s5
	s_min_u32 s4, s4, 0x15d0
	s_cmp_ge_i32 s33, s4
	s_cbranch_scc1 .Lsl4_out
	s_add_u32 s94, s34, 0x1da0000
	s_addc_u32 s95, s35, 0
	v_writelane_b32 v252, s90, 0
	s_add_u32 s4, s34, 0x7a0000
	s_addc_u32 s5, s35, 0
	v_writelane_b32 v252, s91, 1
	v_writelane_b32 v252, s4, 2
	v_lshrrev_b32_e32 v138, 8, v204
	v_and_b32_e32 v139, 0xff, v204
	v_writelane_b32 v252, s5, 3
	s_add_u32 s4, s34, 0x720000
	s_addc_u32 s5, s35, 0
	v_writelane_b32 v252, s4, 4
	v_mul_u32_u24_e32 v140, 0x12000, v138
	v_mov_b32_e32 v129, 0
	v_writelane_b32 v252, s5, 5
	s_add_u32 s4, s34, 0x520000
	s_addc_u32 s5, s35, 0
	s_add_u32 s90, s34, 0x4a0000
	s_addc_u32 s91, s35, 0
	s_add_u32 s96, s34, 0x440000
	s_addc_u32 s97, s35, 0
	s_add_u32 s16, s34, 0x28a0000
	s_addc_u32 s17, s35, 0
	s_add_u32 s18, s0, 0x120
	v_writelane_b32 v252, s4, 6
	s_addc_u32 s19, s1, 0
	s_movk_i32 s8, 0x104
	s_movk_i32 s9, 0xffe0
	s_movk_i32 s10, 0x6000
	s_movk_i32 s11, 0x400
	s_mov_b32 s12, 0xbfb8aa3b
	s_mov_b32 s13, 0x42ce8ed0
	s_mov_b32 s14, 0xc2b17218
	s_movk_i32 s15, 0x1800
	v_mov_b32_e32 v141, 0xfffffd40
	v_mov_b32_e32 v142, 0xb00000
	v_mov_b32_e32 v143, 0x580000
	v_mov_b32_e32 v144, 0x7f800000
	v_writelane_b32 v252, s5, 7
	s_branch .Lsl4_22

.LBB0_1013:
	s_or_b64 exec, exec, s[4:5]
	s_waitcnt lgkmcnt(0)
.LBB0_1014:
	v_mov_b32_e32 v201, 0x24008
	ds_read_b32 v200, v201
	s_waitcnt lgkmcnt(0)
	s_cmp_lg_u32 s88, 0
	s_cbranch_scc1 .Lsl6_out
	s_cmp_lg_u32 s89, 18
	s_cbranch_scc1 .Lsl6_out
	s_load_dword s4, s[0:1], 0x120
	s_load_dwordx16 s[52:67], s[0:1], 0x0
	s_load_dwordx16 s[68:83], s[0:1], 0x80
	s_waitcnt lgkmcnt(0)
	s_add_u32 s98, s34, 0xed10500
	s_addc_u32 s99, s35, 0
	v_mov_b32_e32 v201, 0
	s_lshl_b32 s4, s4, 1
	s_mul_i32 s5, s4, 6
	s_lshl_b32 s33, s2, 1
	s_add_i32 s33, s33, s5
	s_mov_b32 s5, 7
	s_mul_i32 s4, s4, s5
	s_min_u32 s4, s4, 0x15d0
	s_cmp_ge_i32 s33, s4
	s_cbranch_scc1 .Lsl6_out
	s_add_u32 s94, s34, 0x1da0000
	s_addc_u32 s95, s35, 0
	v_writelane_b32 v252, s90, 0
	s_add_u32 s4, s34, 0x7a0000
	s_addc_u32 s5, s35, 0
	v_writelane_b32 v252, s91, 1
	v_writelane_b32 v252, s4, 2
	v_lshrrev_b32_e32 v138, 8, v204
	v_and_b32_e32 v139, 0xff, v204
	v_writelane_b32 v252, s5, 3
	s_add_u32 s4, s34, 0x720000
	s_addc_u32 s5, s35, 0
	v_writelane_b32 v252, s4, 4
	v_mul_u32_u24_e32 v140, 0x12000, v138
	v_mov_b32_e32 v129, 0
	v_writelane_b32 v252, s5, 5
	s_add_u32 s4, s34, 0x520000
	s_addc_u32 s5, s35, 0
	s_add_u32 s90, s34, 0x4a0000
	s_addc_u32 s91, s35, 0
	s_add_u32 s96, s34, 0x440000
	s_addc_u32 s97, s35, 0
	s_add_u32 s16, s34, 0x28a0000
	s_addc_u32 s17, s35, 0
	s_add_u32 s18, s0, 0x120
	v_writelane_b32 v252, s4, 6
	s_addc_u32 s19, s1, 0
	s_movk_i32 s8, 0x104
	s_movk_i32 s9, 0xffe0
	s_movk_i32 s10, 0x6000
	s_movk_i32 s11, 0x400
	s_mov_b32 s12, 0xbfb8aa3b
	s_mov_b32 s13, 0x42ce8ed0
	s_mov_b32 s14, 0xc2b17218
	s_movk_i32 s15, 0x1800
	v_mov_b32_e32 v141, 0xfffffd40
	v_mov_b32_e32 v142, 0xb00000
	v_mov_b32_e32 v143, 0x580000
	v_mov_b32_e32 v144, 0x7f800000
	v_writelane_b32 v252, s5, 7
	s_branch .Lsl6_22

.LBB0_1076:
	s_or_b64 exec, exec, s[4:5]
	s_waitcnt lgkmcnt(0)
.LBB0_1077:
	v_mov_b32_e32 v201, 0x24008
	ds_read_b32 v200, v201
	s_waitcnt lgkmcnt(0)
	s_cmp_lg_u32 s88, 0
	s_cbranch_scc1 .Lsl7_out
	s_cmp_lg_u32 s89, 18
	s_cbranch_scc1 .Lsl7_out
	s_load_dword s4, s[0:1], 0x120
	s_load_dwordx16 s[52:67], s[0:1], 0x0
	s_load_dwordx16 s[68:83], s[0:1], 0x80
	s_waitcnt lgkmcnt(0)
	s_add_u32 s98, s34, 0xed10500
	s_addc_u32 s99, s35, 0
	v_mov_b32_e32 v201, 0
	s_lshl_b32 s4, s4, 1
	s_mul_i32 s5, s4, 8
	s_lshl_b32 s33, s2, 1
	s_add_i32 s33, s33, s5
	s_mov_b32 s5, 9
	s_mul_i32 s4, s4, s5
	s_min_u32 s4, s4, 0x15d0
	s_cmp_ge_i32 s33, s4
	s_cbranch_scc1 .Lsl7_out
	s_add_u32 s94, s34, 0x1da0000
	s_addc_u32 s95, s35, 0
	v_writelane_b32 v252, s90, 0
	s_add_u32 s4, s34, 0x7a0000
	s_addc_u32 s5, s35, 0
	v_writelane_b32 v252, s91, 1
	v_writelane_b32 v252, s4, 2
	v_lshrrev_b32_e32 v138, 8, v204
	v_and_b32_e32 v139, 0xff, v204
	v_writelane_b32 v252, s5, 3
	s_add_u32 s4, s34, 0x720000
	s_addc_u32 s5, s35, 0
	v_writelane_b32 v252, s4, 4
	v_mul_u32_u24_e32 v140, 0x12000, v138
	v_mov_b32_e32 v129, 0
	v_writelane_b32 v252, s5, 5
	s_add_u32 s4, s34, 0x520000
	s_addc_u32 s5, s35, 0
	s_add_u32 s90, s34, 0x4a0000
	s_addc_u32 s91, s35, 0
	s_add_u32 s96, s34, 0x440000
	s_addc_u32 s97, s35, 0
	s_add_u32 s16, s34, 0x28a0000
	s_addc_u32 s17, s35, 0
	s_add_u32 s18, s0, 0x120
	v_writelane_b32 v252, s4, 6
	s_addc_u32 s19, s1, 0
	s_movk_i32 s8, 0x104
	s_movk_i32 s9, 0xffe0
	s_movk_i32 s10, 0x6000
	s_movk_i32 s11, 0x400
	s_mov_b32 s12, 0xbfb8aa3b
	s_mov_b32 s13, 0x42ce8ed0
	s_mov_b32 s14, 0xc2b17218
	s_movk_i32 s15, 0x1800
	v_mov_b32_e32 v141, 0xfffffd40
	v_mov_b32_e32 v142, 0xb00000
	v_mov_b32_e32 v143, 0x580000
	v_mov_b32_e32 v144, 0x7f800000
	v_writelane_b32 v252, s5, 7
	s_branch .Lsl7_22

.LBB0_1139:
	s_or_b64 exec, exec, s[6:7]
	s_waitcnt lgkmcnt(0)
.LBB0_1140:
	v_mov_b32_e32 v201, 0x24008
	ds_read_b32 v200, v201
	s_waitcnt lgkmcnt(0)
	s_cmp_lg_u32 s88, 0
	s_cbranch_scc1 .Lsl8_out
	s_cmp_lg_u32 s89, 18
	s_cbranch_scc1 .Lsl8_out
	s_load_dword s4, s[0:1], 0x120
	s_load_dwordx16 s[52:67], s[0:1], 0x0
	s_load_dwordx16 s[68:83], s[0:1], 0x80
	s_waitcnt lgkmcnt(0)
	s_add_u32 s98, s34, 0xed10500
	s_addc_u32 s99, s35, 0
	v_mov_b32_e32 v201, 0
	s_lshl_b32 s4, s4, 1
	s_mul_i32 s5, s4, 9
	s_lshl_b32 s33, s2, 1
	s_add_i32 s33, s33, s5
	s_mov_b32 s5, 10
	s_mul_i32 s4, s4, s5
	s_min_u32 s4, s4, 0x15d0
	s_cmp_ge_i32 s33, s4
	s_cbranch_scc1 .Lsl8_out
	s_add_u32 s94, s34, 0x1da0000
	s_addc_u32 s95, s35, 0
	v_writelane_b32 v252, s90, 0
	s_add_u32 s4, s34, 0x7a0000
	s_addc_u32 s5, s35, 0
	v_writelane_b32 v252, s91, 1
	v_writelane_b32 v252, s4, 2
	v_lshrrev_b32_e32 v138, 8, v204
	v_and_b32_e32 v139, 0xff, v204
	v_writelane_b32 v252, s5, 3
	s_add_u32 s4, s34, 0x720000
	s_addc_u32 s5, s35, 0
	v_writelane_b32 v252, s4, 4
	v_mul_u32_u24_e32 v140, 0x12000, v138
	v_mov_b32_e32 v129, 0
	v_writelane_b32 v252, s5, 5
	s_add_u32 s4, s34, 0x520000
	s_addc_u32 s5, s35, 0
	s_add_u32 s90, s34, 0x4a0000
	s_addc_u32 s91, s35, 0
	s_add_u32 s96, s34, 0x440000
	s_addc_u32 s97, s35, 0
	s_add_u32 s16, s34, 0x28a0000
	s_addc_u32 s17, s35, 0
	s_add_u32 s18, s0, 0x120
	v_writelane_b32 v252, s4, 6
	s_addc_u32 s19, s1, 0
	s_movk_i32 s8, 0x104
	s_movk_i32 s9, 0xffe0
	s_movk_i32 s10, 0x6000
	s_movk_i32 s11, 0x400
	s_mov_b32 s12, 0xbfb8aa3b
	s_mov_b32 s13, 0x42ce8ed0
	s_mov_b32 s14, 0xc2b17218
	s_movk_i32 s15, 0x1800
	v_mov_b32_e32 v141, 0xfffffd40
	v_mov_b32_e32 v142, 0xb00000
	v_mov_b32_e32 v143, 0x580000
	v_mov_b32_e32 v144, 0x7f800000
	v_writelane_b32 v252, s5, 7
	s_branch .Lsl8_22

.LBB0_1201:
	s_or_b64 exec, exec, s[4:5]
	s_waitcnt lgkmcnt(0)
.LBB0_1202:
	v_mov_b32_e32 v201, 0x24008
	ds_read_b32 v200, v201
	s_waitcnt lgkmcnt(0)
	s_cmp_lg_u32 s88, 0
	s_cbranch_scc1 .Lsl9_out
	s_cmp_lg_u32 s89, 18
	s_cbranch_scc1 .Lsl9_out
	s_load_dword s4, s[0:1], 0x120
	s_load_dwordx16 s[52:67], s[0:1], 0x0
	s_load_dwordx16 s[68:83], s[0:1], 0x80
	s_waitcnt lgkmcnt(0)
	s_add_u32 s98, s34, 0xed10500
	s_addc_u32 s99, s35, 0
	v_mov_b32_e32 v201, 0
	s_lshl_b32 s4, s4, 1
	s_mul_i32 s5, s4, 7
	s_lshl_b32 s33, s2, 1
	s_add_i32 s33, s33, s5
	s_mov_b32 s5, 8
	s_mul_i32 s4, s4, s5
	s_min_u32 s4, s4, 0x15d0
	s_cmp_ge_i32 s33, s4
	s_cbranch_scc1 .Lsl9_out
	s_add_u32 s94, s34, 0x1da0000
	s_addc_u32 s95, s35, 0
	v_writelane_b32 v252, s90, 0
	s_add_u32 s4, s34, 0x7a0000
	s_addc_u32 s5, s35, 0
	v_writelane_b32 v252, s91, 1
	v_writelane_b32 v252, s4, 2
	v_lshrrev_b32_e32 v138, 8, v204
	v_and_b32_e32 v139, 0xff, v204
	v_writelane_b32 v252, s5, 3
	s_add_u32 s4, s34, 0x720000
	s_addc_u32 s5, s35, 0
	v_writelane_b32 v252, s4, 4
	v_mul_u32_u24_e32 v140, 0x12000, v138
	v_mov_b32_e32 v129, 0
	v_writelane_b32 v252, s5, 5
	s_add_u32 s4, s34, 0x520000
	s_addc_u32 s5, s35, 0
	s_add_u32 s90, s34, 0x4a0000
	s_addc_u32 s91, s35, 0
	s_add_u32 s96, s34, 0x440000
	s_addc_u32 s97, s35, 0
	s_add_u32 s16, s34, 0x28a0000
	s_addc_u32 s17, s35, 0
	s_add_u32 s18, s0, 0x120
	v_writelane_b32 v252, s4, 6
	s_addc_u32 s19, s1, 0
	s_movk_i32 s8, 0x104
	s_movk_i32 s9, 0xffe0
	s_movk_i32 s10, 0x6000
	s_movk_i32 s11, 0x400
	s_mov_b32 s12, 0xbfb8aa3b
	s_mov_b32 s13, 0x42ce8ed0
	s_mov_b32 s14, 0xc2b17218
	s_movk_i32 s15, 0x1800
	v_mov_b32_e32 v141, 0xfffffd40
	v_mov_b32_e32 v142, 0xb00000
	v_mov_b32_e32 v143, 0x580000
	v_mov_b32_e32 v144, 0x7f800000
	v_writelane_b32 v252, s5, 7
	s_branch .Lsl9_22

.LBB0_1264:
	s_or_b64 exec, exec, s[4:5]
	s_waitcnt lgkmcnt(0)
.LBB0_1265:
	v_mov_b32_e32 v201, 0x24008
	ds_read_b32 v200, v201
	s_waitcnt lgkmcnt(0)
	s_cmp_lg_u32 s88, 0
	s_cbranch_scc1 .Lsl10_out
	s_cmp_lg_u32 s89, 18
	s_cbranch_scc1 .Lsl10_out
	s_load_dword s4, s[0:1], 0x120
	s_load_dwordx16 s[52:67], s[0:1], 0x0
	s_load_dwordx16 s[68:83], s[0:1], 0x80
	s_waitcnt lgkmcnt(0)
	s_add_u32 s98, s34, 0xed10500
	s_addc_u32 s99, s35, 0
	v_mov_b32_e32 v201, 0
	s_lshl_b32 s4, s4, 1
	s_mul_i32 s5, s4, 10
	s_lshl_b32 s33, s2, 1
	s_add_i32 s33, s33, s5
	s_mov_b32 s5, 11
	s_mul_i32 s4, s4, s5
	s_min_u32 s4, s4, 0x15d0
	s_cmp_ge_i32 s33, s4
	s_cbranch_scc1 .Lsl10_out
	s_add_u32 s94, s34, 0x1da0000
	s_addc_u32 s95, s35, 0
	v_writelane_b32 v252, s90, 0
	s_add_u32 s4, s34, 0x7a0000
	s_addc_u32 s5, s35, 0
	v_writelane_b32 v252, s91, 1
	v_writelane_b32 v252, s4, 2
	v_lshrrev_b32_e32 v138, 8, v204
	v_and_b32_e32 v139, 0xff, v204
	v_writelane_b32 v252, s5, 3
	s_add_u32 s4, s34, 0x720000
	s_addc_u32 s5, s35, 0
	v_writelane_b32 v252, s4, 4
	v_mul_u32_u24_e32 v140, 0x12000, v138
	v_mov_b32_e32 v129, 0
	v_writelane_b32 v252, s5, 5
	s_add_u32 s4, s34, 0x520000
	s_addc_u32 s5, s35, 0
	s_add_u32 s90, s34, 0x4a0000
	s_addc_u32 s91, s35, 0
	s_add_u32 s96, s34, 0x440000
	s_addc_u32 s97, s35, 0
	s_add_u32 s16, s34, 0x28a0000
	s_addc_u32 s17, s35, 0
	s_add_u32 s18, s0, 0x120
	v_writelane_b32 v252, s4, 6
	s_addc_u32 s19, s1, 0
	s_movk_i32 s8, 0x104
	s_movk_i32 s9, 0xffe0
	s_movk_i32 s10, 0x6000
	s_movk_i32 s11, 0x400
	s_mov_b32 s12, 0xbfb8aa3b
	s_mov_b32 s13, 0x42ce8ed0
	s_mov_b32 s14, 0xc2b17218
	s_movk_i32 s15, 0x1800
	v_mov_b32_e32 v141, 0xfffffd40
	v_mov_b32_e32 v142, 0xb00000
	v_mov_b32_e32 v143, 0x580000
	v_mov_b32_e32 v144, 0x7f800000
	v_writelane_b32 v252, s5, 7
	s_branch .Lsl10_22
